# P16: the last 4 of each workgroup's 11 output tiles stored cached (rest keep nt) so the newest part of U is still in the memory-side cache when the conv phase reads it
# speedup vs baseline: 1.0111x; 1.0111x over previous
.LBB0_1338:
	s_cmp_ge_u32 s36, 8
	s_cbranch_scc1 .Lep16_tail
	s_lshl_b32 s11, s18, 8
	v_mbcnt_lo_u32_b32 v144, -1, 0
	v_mbcnt_hi_u32_b32 v144, -1, v144
	s_add_i32 s11, s11, s37
	v_and_or_b32 v152, v144, 15, s11
	s_lshl_b32 s11, s44, 8
	v_ashrrev_i32_e32 v144, 1, v144
	v_and_b32_e32 v144, -8, v144
	s_or_b32 s11, s11, s38
	v_add_u32_e32 v144, s11, v144
	v_ashrrev_i32_e32 v145, 31, v144
	v_lshl_add_u64 v[144:145], v[144:145], 1, s[4:5]
	v_mad_i64_i32 v[150:151], s[20:21], v152, s43, v[144:145]
	v_cvt_pk_bf16_f32 v124, v124, v125
	v_cvt_pk_bf16_f32 v125, v126, v127
	v_cvt_pk_bf16_f32 v126, v120, v121
	v_cvt_pk_bf16_f32 v127, v122, v123
	global_store_dwordx4 v[150:151], v[124:127], off nt
	v_cvt_pk_bf16_f32 v112, v112, v113
	v_cvt_pk_bf16_f32 v113, v114, v115
	v_cvt_pk_bf16_f32 v114, v104, v105
	v_or_b32_e32 v104, 16, v152
	v_cvt_pk_bf16_f32 v115, v106, v107
	global_store_dwordx4 v[150:151], v[112:115], off offset:256 nt
	s_andn2_b64 vcc, exec, s[2:3]
	s_mov_b64 s[2:3], -1
	v_mad_i64_i32 v[112:113], s[20:21], v104, s43, v[144:145]
	v_cvt_pk_bf16_f32 v104, v116, v117
	v_cvt_pk_bf16_f32 v105, v118, v119
	v_cvt_pk_bf16_f32 v106, v108, v109
	v_cvt_pk_bf16_f32 v107, v110, v111
	global_store_dwordx4 v[112:113], v[104:107], off nt
	v_cvt_pk_bf16_f32 v96, v96, v97
	v_cvt_pk_bf16_f32 v97, v98, v99
	v_cvt_pk_bf16_f32 v98, v88, v89
	v_or_b32_e32 v88, 32, v152
	v_cvt_pk_bf16_f32 v99, v90, v91
	global_store_dwordx4 v[112:113], v[96:99], off offset:256 nt
	s_nop 1
	v_mad_i64_i32 v[96:97], s[20:21], v88, s43, v[144:145]
	v_cvt_pk_bf16_f32 v88, v100, v101
	v_cvt_pk_bf16_f32 v89, v102, v103
	v_cvt_pk_bf16_f32 v90, v92, v93
	v_cvt_pk_bf16_f32 v91, v94, v95
	global_store_dwordx4 v[96:97], v[88:91], off nt
	v_cvt_pk_bf16_f32 v80, v80, v81
	v_cvt_pk_bf16_f32 v81, v82, v83
	v_cvt_pk_bf16_f32 v82, v72, v73
	v_or_b32_e32 v72, 48, v152
	v_cvt_pk_bf16_f32 v83, v74, v75
	global_store_dwordx4 v[96:97], v[80:83], off offset:256 nt
	s_nop 1
	v_mad_i64_i32 v[80:81], s[20:21], v72, s43, v[144:145]
	v_cvt_pk_bf16_f32 v72, v84, v85
	v_cvt_pk_bf16_f32 v73, v86, v87
	v_cvt_pk_bf16_f32 v74, v76, v77
	v_cvt_pk_bf16_f32 v75, v78, v79
	global_store_dwordx4 v[80:81], v[72:75], off nt
	v_cvt_pk_bf16_f32 v68, v68, v69
	v_cvt_pk_bf16_f32 v69, v70, v71
	v_cvt_pk_bf16_f32 v70, v64, v65
	v_add_u32_e32 v64, 0x80, v152
	v_cvt_pk_bf16_f32 v71, v66, v67
	global_store_dwordx4 v[80:81], v[68:71], off offset:256 nt
	v_mad_i64_i32 v[64:65], s[20:21], v64, s43, v[144:145]
	v_cvt_pk_bf16_f32 v60, v60, v61
	v_cvt_pk_bf16_f32 v61, v62, v63
	v_cvt_pk_bf16_f32 v62, v56, v57
	v_cvt_pk_bf16_f32 v63, v58, v59
	global_store_dwordx4 v[64:65], v[60:63], off nt
	v_cvt_pk_bf16_f32 v48, v48, v49
	v_cvt_pk_bf16_f32 v49, v50, v51
	v_cvt_pk_bf16_f32 v50, v40, v41
	v_add_u32_e32 v40, 0x90, v152
	v_cvt_pk_bf16_f32 v51, v42, v43
	global_store_dwordx4 v[64:65], v[48:51], off offset:256 nt
	s_nop 1
	v_mad_i64_i32 v[48:49], s[20:21], v40, s43, v[144:145]
	v_cvt_pk_bf16_f32 v40, v52, v53
	v_cvt_pk_bf16_f32 v41, v54, v55
	v_cvt_pk_bf16_f32 v42, v44, v45
	v_cvt_pk_bf16_f32 v43, v46, v47
	global_store_dwordx4 v[48:49], v[40:43], off nt
	v_cvt_pk_bf16_f32 v32, v32, v33
	v_cvt_pk_bf16_f32 v33, v34, v35
	v_cvt_pk_bf16_f32 v34, v24, v25
	v_add_u32_e32 v24, 0xa0, v152
	v_cvt_pk_bf16_f32 v35, v26, v27
	global_store_dwordx4 v[48:49], v[32:35], off offset:256 nt
	s_nop 1
	v_mad_i64_i32 v[32:33], s[20:21], v24, s43, v[144:145]
	v_cvt_pk_bf16_f32 v24, v36, v37
	v_cvt_pk_bf16_f32 v25, v38, v39
	v_cvt_pk_bf16_f32 v26, v28, v29
	v_cvt_pk_bf16_f32 v27, v30, v31
	global_store_dwordx4 v[32:33], v[24:27], off nt
	v_cvt_pk_bf16_f32 v16, v16, v17
	v_cvt_pk_bf16_f32 v17, v18, v19
	v_cvt_pk_bf16_f32 v18, v8, v9
	v_add_u32_e32 v8, 0xb0, v152
	v_cvt_pk_bf16_f32 v19, v10, v11
	global_store_dwordx4 v[32:33], v[16:19], off offset:256 nt
	s_nop 1
	v_mad_i64_i32 v[16:17], s[20:21], v8, s43, v[144:145]
	v_cvt_pk_bf16_f32 v8, v20, v21
	v_cvt_pk_bf16_f32 v9, v22, v23
	v_cvt_pk_bf16_f32 v10, v12, v13
	v_cvt_pk_bf16_f32 v11, v14, v15
	global_store_dwordx4 v[16:17], v[8:11], off nt
	v_cvt_pk_bf16_f32 v4, v4, v5
	v_cvt_pk_bf16_f32 v5, v6, v7
	v_cvt_pk_bf16_f32 v6, v0, v1
	v_cvt_pk_bf16_f32 v7, v2, v3
	global_store_dwordx4 v[16:17], v[4:7], off offset:256 nt
	s_branch .Lep16_join
.Lep16_tail:
	s_lshl_b32 s11, s18, 8
	v_mbcnt_lo_u32_b32 v144, -1, 0
	v_mbcnt_hi_u32_b32 v144, -1, v144
	s_add_i32 s11, s11, s37
	v_and_or_b32 v152, v144, 15, s11
	s_lshl_b32 s11, s44, 8
	v_ashrrev_i32_e32 v144, 1, v144
	v_and_b32_e32 v144, -8, v144
	s_or_b32 s11, s11, s38
	v_add_u32_e32 v144, s11, v144
	v_ashrrev_i32_e32 v145, 31, v144
	v_lshl_add_u64 v[144:145], v[144:145], 1, s[4:5]
	v_mad_i64_i32 v[150:151], s[20:21], v152, s43, v[144:145]
	v_cvt_pk_bf16_f32 v124, v124, v125
	v_cvt_pk_bf16_f32 v125, v126, v127
	v_cvt_pk_bf16_f32 v126, v120, v121
	v_cvt_pk_bf16_f32 v127, v122, v123
	global_store_dwordx4 v[150:151], v[124:127], off
	v_cvt_pk_bf16_f32 v112, v112, v113
	v_cvt_pk_bf16_f32 v113, v114, v115
	v_cvt_pk_bf16_f32 v114, v104, v105
	v_or_b32_e32 v104, 16, v152
	v_cvt_pk_bf16_f32 v115, v106, v107
	global_store_dwordx4 v[150:151], v[112:115], off offset:256
	s_andn2_b64 vcc, exec, s[2:3]
	s_mov_b64 s[2:3], -1
	v_mad_i64_i32 v[112:113], s[20:21], v104, s43, v[144:145]
	v_cvt_pk_bf16_f32 v104, v116, v117
	v_cvt_pk_bf16_f32 v105, v118, v119
	v_cvt_pk_bf16_f32 v106, v108, v109
	v_cvt_pk_bf16_f32 v107, v110, v111
	global_store_dwordx4 v[112:113], v[104:107], off
	v_cvt_pk_bf16_f32 v96, v96, v97
	v_cvt_pk_bf16_f32 v97, v98, v99
	v_cvt_pk_bf16_f32 v98, v88, v89
	v_or_b32_e32 v88, 32, v152
	v_cvt_pk_bf16_f32 v99, v90, v91
	global_store_dwordx4 v[112:113], v[96:99], off offset:256
	s_nop 1
	v_mad_i64_i32 v[96:97], s[20:21], v88, s43, v[144:145]
	v_cvt_pk_bf16_f32 v88, v100, v101
	v_cvt_pk_bf16_f32 v89, v102, v103
	v_cvt_pk_bf16_f32 v90, v92, v93
	v_cvt_pk_bf16_f32 v91, v94, v95
	global_store_dwordx4 v[96:97], v[88:91], off
	v_cvt_pk_bf16_f32 v80, v80, v81
	v_cvt_pk_bf16_f32 v81, v82, v83
	v_cvt_pk_bf16_f32 v82, v72, v73
	v_or_b32_e32 v72, 48, v152
	v_cvt_pk_bf16_f32 v83, v74, v75
	global_store_dwordx4 v[96:97], v[80:83], off offset:256
	s_nop 1
	v_mad_i64_i32 v[80:81], s[20:21], v72, s43, v[144:145]
	v_cvt_pk_bf16_f32 v72, v84, v85
	v_cvt_pk_bf16_f32 v73, v86, v87
	v_cvt_pk_bf16_f32 v74, v76, v77
	v_cvt_pk_bf16_f32 v75, v78, v79
	global_store_dwordx4 v[80:81], v[72:75], off
	v_cvt_pk_bf16_f32 v68, v68, v69
	v_cvt_pk_bf16_f32 v69, v70, v71
	v_cvt_pk_bf16_f32 v70, v64, v65
	v_add_u32_e32 v64, 0x80, v152
	v_cvt_pk_bf16_f32 v71, v66, v67
	global_store_dwordx4 v[80:81], v[68:71], off offset:256
	v_mad_i64_i32 v[64:65], s[20:21], v64, s43, v[144:145]
	v_cvt_pk_bf16_f32 v60, v60, v61
	v_cvt_pk_bf16_f32 v61, v62, v63
	v_cvt_pk_bf16_f32 v62, v56, v57
	v_cvt_pk_bf16_f32 v63, v58, v59
	global_store_dwordx4 v[64:65], v[60:63], off
	v_cvt_pk_bf16_f32 v48, v48, v49
	v_cvt_pk_bf16_f32 v49, v50, v51
	v_cvt_pk_bf16_f32 v50, v40, v41
	v_add_u32_e32 v40, 0x90, v152
	v_cvt_pk_bf16_f32 v51, v42, v43
	global_store_dwordx4 v[64:65], v[48:51], off offset:256
	s_nop 1
	v_mad_i64_i32 v[48:49], s[20:21], v40, s43, v[144:145]
	v_cvt_pk_bf16_f32 v40, v52, v53
	v_cvt_pk_bf16_f32 v41, v54, v55
	v_cvt_pk_bf16_f32 v42, v44, v45
	v_cvt_pk_bf16_f32 v43, v46, v47
	global_store_dwordx4 v[48:49], v[40:43], off
	v_cvt_pk_bf16_f32 v32, v32, v33
	v_cvt_pk_bf16_f32 v33, v34, v35
	v_cvt_pk_bf16_f32 v34, v24, v25
	v_add_u32_e32 v24, 0xa0, v152
	v_cvt_pk_bf16_f32 v35, v26, v27
	global_store_dwordx4 v[48:49], v[32:35], off offset:256
	s_nop 1
	v_mad_i64_i32 v[32:33], s[20:21], v24, s43, v[144:145]
	v_cvt_pk_bf16_f32 v24, v36, v37
	v_cvt_pk_bf16_f32 v25, v38, v39
	v_cvt_pk_bf16_f32 v26, v28, v29
	v_cvt_pk_bf16_f32 v27, v30, v31
	global_store_dwordx4 v[32:33], v[24:27], off
	v_cvt_pk_bf16_f32 v16, v16, v17
	v_cvt_pk_bf16_f32 v17, v18, v19
	v_cvt_pk_bf16_f32 v18, v8, v9
	v_add_u32_e32 v8, 0xb0, v152
	v_cvt_pk_bf16_f32 v19, v10, v11
	global_store_dwordx4 v[32:33], v[16:19], off offset:256
	s_nop 1
	v_mad_i64_i32 v[16:17], s[20:21], v8, s43, v[144:145]
	v_cvt_pk_bf16_f32 v8, v20, v21
	v_cvt_pk_bf16_f32 v9, v22, v23
	v_cvt_pk_bf16_f32 v10, v12, v13
	v_cvt_pk_bf16_f32 v11, v14, v15
	global_store_dwordx4 v[16:17], v[8:11], off
	v_cvt_pk_bf16_f32 v4, v4, v5
	v_cvt_pk_bf16_f32 v5, v6, v7
	v_cvt_pk_bf16_f32 v6, v0, v1
	v_cvt_pk_bf16_f32 v7, v2, v3
	global_store_dwordx4 v[16:17], v[4:7], off offset:256
.Lep16_join:
	s_cbranch_vccnz .LBB0_1331
	s_andn2_b64 vcc, exec, s[0:1]
	s_cbranch_vccnz .LBB0_1330
	s_barrier
	s_branch .LBB0_1330
.LBB0_1341:
	v_readlane_b32 s0, v254, 0
	v_readlane_b32 s1, v254, 1
	s_waitcnt vmcnt(0)
	s_barrier
	s_load_dwordx4 s[40:43], s[0:1], 0xe0
	v_readlane_b32 s36, v254, 46
	v_readlane_b32 s37, v254, 47
	s_waitcnt lgkmcnt(0)
	v_readlane_b32 s40, v255, 29
